# grid barrier second stage flattened: XCD leaders bump one global counter (no return), all blocks poll it; drops TOPGEN/XGEN hops
# baseline (speedup 1.0000x reference)
.LBB0_311:
	s_waitcnt lgkmcnt(0)
	v_readlane_b32 s16, v254, 56
	v_readlane_b32 s4, v252, 14
	v_readlane_b32 s5, v252, 15
	v_mov_b32_e32 v4, 1
	v_mov_b32_e32 v6, s16
	ds_read_b32 v5, v6 offset:8
	s_nop 3
	global_atomic_add v4, v3, v4, s[4:5] sc0
	s_waitcnt vmcnt(0) lgkmcnt(0)
	v_add_u32_e32 v5, 1, v5
	v_mul_lo_u32 v1, v5, v2
	v_mul_lo_u32 v0, v5, v0
	v_add_u32_e32 v4, 1, v4
	ds_write_b32 v6, v5 offset:8
	v_readlane_b32 s4, v252, 18
	v_readlane_b32 s5, v252, 19
	v_readfirstlane_b32 s20, v1
	v_readfirstlane_b32 s21, v4
	v_readfirstlane_b32 s17, v0
	s_cmp_lg_u32 s21, s20
	s_cbranch_scc1 .Lxb0_poll
	buffer_wbl2 sc1
	s_waitcnt vmcnt(0)
	v_mov_b32_e32 v4, 1
	global_atomic_add v3, v4, s[4:5]
.Lxb0_poll:
	s_mov_b32 s16, 0
.Lxb0_loop:
	global_load_dword v4, v3, s[4:5] sc1
	s_waitcnt vmcnt(0)
	v_readfirstlane_b32 s21, v4
	s_cmp_ge_u32 s21, s17
	s_cbranch_scc1 .Lxb0_done
	s_sleep 1
	s_add_i32 s16, s16, 1
	s_cmp_lt_u32 s16, 0x8000
	s_cbranch_scc1 .Lxb0_loop
.Lxb0_done:
	buffer_inv sc1
	s_waitcnt vmcnt(0) lgkmcnt(0)

.Lxb8_done:
	buffer_inv sc1
	s_waitcnt vmcnt(0) lgkmcnt(0)
	s_mov_b64 s[4:5], 0
	s_getpc_b64 s[98:99]
